# phase A: blocks with blockIdx bit 8 start half a K-step later so co-resident blocks do not issue stage DMAs / MFMA bursts in lock step
# speedup vs baseline: 1.0022x; 1.0022x over previous
; DI void phase_inproj(const Params& p, int layer, char*) {
;   const bfr* A = (const bfr*)(p.ws + W_HN);
;   const bfr* Bt = (const bfr*)(p.ws + W_WINT) + (long)layer * NPAD * 1024;
;   constexpr int NTM = MPAD / 128, NTN = NPAD / 128;
;   const int rank = sh_xinfo[0], nloc = sh_xinfo[1], ia = sh_xinfo[2], na = sh_xinfo[3];
;   const int nbase = NTN / na, nrem = NTN % na;
;   const int nn = nbase + (ia < nrem ? 1 : 0), n0 = ia * nbase + min(ia, nrem);
;   const int target = (NTM * NTN + na - 1) / na;
;   const int keep = min(NTM * nn, target);
;   int poff = 0, stot = 0;
;   for (int a = 0; a < na; ++a) {
;     const int o = NTM * (nbase + (a < nrem ? 1 : 0)), kp = min(o, target);
;     if (a < ia) poff += target - kp;
;     stot += o - kp;
;   }
;   const int dend = min(poff + (target - keep), stot);
;   const int kown = rank < keep ? (keep - rank + nloc - 1) / nloc : 0;
;   auto get_tile = [&](int k, int& tm_, int& tn_) -> bool {
;     if (k < kown) { const int i = rank + k * nloc; tm_ = i / nn; tn_ = n0 + (i - tm_ * nn); return true; }
;     const int e = poff + rank + (k - kown) * nloc;
;     if (e >= dend) return false;
;     int accs = 0;
;     for (int a = 0; a < na; ++a) {
;       const int nna = nbase + (a < nrem ? 1 : 0), o = NTM * nna, kp = min(o, target), sp = o - kp;
;       if (e < accs + sp) {
;         const int i = kp + (e - accs);
;         tm_ = i / nna;
;         tn_ = a * nbase + min(a, nrem) + (i - tm_ * nna);
;         return true;
;       }
;       accs += sp;
;     }
;     return false;
;   };
;   bool first = true;
;   int tm = 0, tn = 0;
;   bool have = get_tile(0, tm, tn);
.LBB0_213:
	s_andn2_b64 vcc, exec, s[4:5]
	s_cbranch_vccnz .LBB0_1937
	v_readlane_b32 s4, v249, 54
	s_nop 0
	s_bitcmp1_b32 s4, 8
	s_cbranch_scc0 .Ldph_a
	s_sleep 19
.Ldph_a:
	s_ashr_i32 s1, s0, 31
	v_readlane_b32 s44, v249, 0
	v_readlane_b32 s45, v249, 1
	s_add_u32 s12, s44, s0
	v_readlane_b32 s16, v249, 38
	s_addc_u32 s13, s45, s1
	s_lshl_b64 s[2:3], s[0:1], 2
	v_readlane_b32 s30, v249, 52
	v_readlane_b32 s31, v249, 53
	s_add_u32 s14, s30, s2
	s_addc_u32 s15, s31, s3
	v_readlane_b32 s17, v249, 39
	s_add_u32 s16, s12, 0x6cc8400
	s_addc_u32 s17, s13, 0
	s_mul_i32 s3, s69, 0xec0000
	s_mul_hi_i32 s2, s69, 0xec0000
	s_add_u32 s4, s12, s3
	v_readlane_b32 s18, v249, 40
	s_addc_u32 s5, s13, s2
	v_readlane_b32 s19, v249, 41
	s_add_u32 s18, s4, 0x48400
	v_readlane_b32 s20, v249, 42
	s_addc_u32 s19, s5, 0
	s_add_i32 s63, s34, s54
	s_lshl_b32 s64, s69, 2
	v_readlane_b32 s21, v249, 43
	s_add_u32 s20, s12, 0xb9d8400
	v_readlane_b32 s22, v249, 44
	s_addc_u32 s21, s13, 0
	v_readlane_b32 s23, v249, 45
	s_add_u32 s22, s12, 0xfe9cc00
	v_readlane_b32 s24, v249, 46
	s_addc_u32 s23, s13, 0
	v_readlane_b32 s25, v249, 47
	s_add_u32 s24, s12, 0xed7cc00
	v_readlane_b32 s26, v249, 48
	s_addc_u32 s25, s13, 0
	v_readlane_b32 s27, v249, 49
	s_add_u32 s26, s12, 0xdc5cc00
	v_readlane_b32 s28, v249, 50
	s_addc_u32 s27, s13, 0
	v_readlane_b32 s29, v249, 51
	s_add_u32 s28, s12, 0xcb3cc00
	s_addc_u32 s29, s13, 0
	s_add_u32 s30, s12, 0xba1cc00
	s_addc_u32 s31, s13, 0
	s_add_u32 s34, s12, 0x8000
	s_addc_u32 s35, s13, 0
	s_add_u32 s36, s12, 0xb148400
	s_addc_u32 s37, s13, 0
	s_add_u32 s38, s12, 0xa028400
	s_addc_u32 s39, s13, 0
	s_add_u32 s40, s12, 0x1757cc00
	s_addc_u32 s41, s13, 0
	s_add_u32 s42, s12, 0x8f08400
	s_addc_u32 s43, s13, 0
	s_abs_i32 s65, s59
	v_cvt_f32_u32_e32 v0, s65
	s_sub_i32 s4, 0, s65
	s_ashr_i32 s67, s59, 31
	s_add_i32 s71, s71, -1
	v_rcp_iflag_f32_e32 v0, v0
	s_mov_b32 s66, 0
	s_mul_i32 s69, s69, 12
	v_readlane_b32 s46, v249, 2
	v_mul_f32_e32 v0, 0x4f7ffffe, v0
	v_cvt_u32_f32_e32 v0, v0
	v_readlane_b32 s47, v249, 3
	v_readfirstlane_b32 s5, v0
	s_mul_i32 s4, s4, s5
	s_mul_hi_u32 s4, s5, s4
	s_add_i32 s68, s5, s4
	s_sub_i32 s4, 1, s60
	s_mul_i32 s4, s55, s4
	s_add_i32 s70, s63, s4
	s_add_u32 s0, s3, s0
	s_addc_u32 s1, s2, s1
	s_add_u32 s44, s44, s0
	s_addc_u32 s45, s45, s1
	s_mov_b64 s[2:3], -1
	s_branch .LBB0_217
